# in-projection GEMM epilogue staged through LDS: full 512-byte row segments per store instruction, no lane-exchange round trips
# speedup vs baseline: 1.0064x; 1.0064x over previous
.LBB0_220:
	v_readlane_b32 s70, v254, 18
	v_readlane_b32 s71, v254, 19
	v_readlane_b32 s68, v254, 16
	v_readlane_b32 s69, v254, 17
	v_and_b32_e32 v131, 63, v180
	v_lshrrev_b32_e32 v132, 6, v180
	v_and_b32_e32 v133, 15, v131
	v_lshrrev_b32_e32 v134, 4, v131
	v_lshrrev_b32_e32 v135, 2, v132
	v_and_b32_e32 v136, 3, v132
	v_lshl_add_u32 v128, v135, 6, v133
	v_mul_u32_u24_e32 v128, 0x210, v128
	v_lshl_add_u32 v128, v136, 6, v128
	v_lshl_add_u32 v128, v134, 3, v128
	v_lshrrev_b32_e32 v137, 5, v131
	v_lshl_add_u32 v137, v132, 4, v137
	v_mul_u32_u24_e32 v129, 0x210, v137
	v_and_b32_e32 v138, 31, v131
	v_lshl_add_u32 v129, v138, 4, v129
	v_mul_u32_u24_e32 v130, 0x5040, v137
	v_lshl_add_u32 v130, v138, 4, v130
	s_mul_i32 s1, s16, 0x5040
	s_lshl_b32 s25, s0, 1
	s_add_u32 s1, s1, s25
	s_add_u32 s20, s70, s1
	s_addc_u32 s21, s71, 0
	s_mov_b32 s24, 0xa080
	v_cvt_pk_bf16_f32 v146, v124, v125
	v_cvt_pk_bf16_f32 v147, v126, v127
	ds_write_b64 v128, v[146:147]
	v_cvt_pk_bf16_f32 v148, v120, v121
	v_cvt_pk_bf16_f32 v149, v122, v123
	ds_write_b64 v128, v[148:149] offset:32
	v_cvt_pk_bf16_f32 v150, v116, v117
	v_cvt_pk_bf16_f32 v151, v118, v119
	ds_write_b64 v128, v[150:151] offset:256
	v_cvt_pk_bf16_f32 v152, v112, v113
	v_cvt_pk_bf16_f32 v153, v114, v115
	ds_write_b64 v128, v[152:153] offset:288
	v_cvt_pk_bf16_f32 v154, v108, v109
	v_cvt_pk_bf16_f32 v155, v110, v111
	ds_write_b64 v128, v[154:155] offset:8448
	v_cvt_pk_bf16_f32 v156, v104, v105
	v_cvt_pk_bf16_f32 v157, v106, v107
	ds_write_b64 v128, v[156:157] offset:8480
	v_cvt_pk_bf16_f32 v158, v100, v101
	v_cvt_pk_bf16_f32 v159, v102, v103
	ds_write_b64 v128, v[158:159] offset:8704
	v_cvt_pk_bf16_f32 v160, v96, v97
	v_cvt_pk_bf16_f32 v161, v98, v99
	ds_write_b64 v128, v[160:161] offset:8736
	v_cvt_pk_bf16_f32 v146, v92, v93
	v_cvt_pk_bf16_f32 v147, v94, v95
	ds_write_b64 v128, v[146:147] offset:16896
	v_cvt_pk_bf16_f32 v148, v88, v89
	v_cvt_pk_bf16_f32 v149, v90, v91
	ds_write_b64 v128, v[148:149] offset:16928
	v_cvt_pk_bf16_f32 v150, v84, v85
	v_cvt_pk_bf16_f32 v151, v86, v87
	ds_write_b64 v128, v[150:151] offset:17152
	v_cvt_pk_bf16_f32 v152, v80, v81
	v_cvt_pk_bf16_f32 v153, v82, v83
	ds_write_b64 v128, v[152:153] offset:17184
	v_cvt_pk_bf16_f32 v154, v76, v77
	v_cvt_pk_bf16_f32 v155, v78, v79
	ds_write_b64 v128, v[154:155] offset:25344
	v_cvt_pk_bf16_f32 v156, v72, v73
	v_cvt_pk_bf16_f32 v157, v74, v75
	ds_write_b64 v128, v[156:157] offset:25376
	v_cvt_pk_bf16_f32 v158, v68, v69
	v_cvt_pk_bf16_f32 v159, v70, v71
	ds_write_b64 v128, v[158:159] offset:25600
	v_cvt_pk_bf16_f32 v160, v64, v65
	v_cvt_pk_bf16_f32 v161, v66, v67
	ds_write_b64 v128, v[160:161] offset:25632
	s_waitcnt lgkmcnt(0)
	s_barrier
	ds_read_b128 v[184:187], v129
	ds_read_b128 v[188:191], v129 offset:1056
	ds_read_b128 v[192:195], v129 offset:2112
	ds_read_b128 v[196:199], v129 offset:3168
	ds_read_b128 v[200:203], v129 offset:4224
	ds_read_b128 v[204:207], v129 offset:5280
	ds_read_b128 v[208:211], v129 offset:6336
	ds_read_b128 v[212:215], v129 offset:7392
	s_waitcnt lgkmcnt(7)
	global_store_dwordx4 v130, v[184:187], s[20:21]
	v_add_u32_e32 v130, s24, v130
	s_waitcnt lgkmcnt(6)
	global_store_dwordx4 v130, v[188:191], s[20:21]
	v_add_u32_e32 v130, s24, v130
	s_waitcnt lgkmcnt(5)
	global_store_dwordx4 v130, v[192:195], s[20:21]
	v_add_u32_e32 v130, s24, v130
	s_waitcnt lgkmcnt(4)
	global_store_dwordx4 v130, v[196:199], s[20:21]
	v_add_u32_e32 v130, s24, v130
	s_waitcnt lgkmcnt(3)
	global_store_dwordx4 v130, v[200:203], s[20:21]
	v_add_u32_e32 v130, s24, v130
	s_waitcnt lgkmcnt(2)
	global_store_dwordx4 v130, v[204:207], s[20:21]
	v_add_u32_e32 v130, s24, v130
	s_waitcnt lgkmcnt(1)
	global_store_dwordx4 v130, v[208:211], s[20:21]
	v_add_u32_e32 v130, s24, v130
	s_waitcnt lgkmcnt(0)
	global_store_dwordx4 v130, v[212:215], s[20:21]
	v_add_u32_e32 v130, s24, v130
	v_add_u32_e32 v130, 0x231c00, v130
	s_barrier
	v_cvt_pk_bf16_f32 v146, v60, v61
	v_cvt_pk_bf16_f32 v147, v62, v63
	ds_write_b64 v128, v[146:147]
	v_cvt_pk_bf16_f32 v148, v56, v57
	v_cvt_pk_bf16_f32 v149, v58, v59
	ds_write_b64 v128, v[148:149] offset:32
	v_cvt_pk_bf16_f32 v150, v52, v53
	v_cvt_pk_bf16_f32 v151, v54, v55
	ds_write_b64 v128, v[150:151] offset:256
	v_cvt_pk_bf16_f32 v152, v48, v49
	v_cvt_pk_bf16_f32 v153, v50, v51
	ds_write_b64 v128, v[152:153] offset:288
	v_cvt_pk_bf16_f32 v154, v44, v45
	v_cvt_pk_bf16_f32 v155, v46, v47
	ds_write_b64 v128, v[154:155] offset:8448
	v_cvt_pk_bf16_f32 v156, v40, v41
	v_cvt_pk_bf16_f32 v157, v42, v43
	ds_write_b64 v128, v[156:157] offset:8480
	v_cvt_pk_bf16_f32 v158, v36, v37
	v_cvt_pk_bf16_f32 v159, v38, v39
	ds_write_b64 v128, v[158:159] offset:8704
	v_cvt_pk_bf16_f32 v160, v32, v33
	v_cvt_pk_bf16_f32 v161, v34, v35
	ds_write_b64 v128, v[160:161] offset:8736
	v_cvt_pk_bf16_f32 v146, v28, v29
	v_cvt_pk_bf16_f32 v147, v30, v31
	ds_write_b64 v128, v[146:147] offset:16896
	v_cvt_pk_bf16_f32 v148, v24, v25
	v_cvt_pk_bf16_f32 v149, v26, v27
	ds_write_b64 v128, v[148:149] offset:16928
	v_cvt_pk_bf16_f32 v150, v20, v21
	v_cvt_pk_bf16_f32 v151, v22, v23
	ds_write_b64 v128, v[150:151] offset:17152
	v_cvt_pk_bf16_f32 v152, v16, v17
	v_cvt_pk_bf16_f32 v153, v18, v19
	ds_write_b64 v128, v[152:153] offset:17184
	v_cvt_pk_bf16_f32 v154, v12, v13
	v_cvt_pk_bf16_f32 v155, v14, v15
	ds_write_b64 v128, v[154:155] offset:25344
	v_cvt_pk_bf16_f32 v156, v8, v9
	v_cvt_pk_bf16_f32 v157, v10, v11
	ds_write_b64 v128, v[156:157] offset:25376
	v_cvt_pk_bf16_f32 v158, v4, v5
	v_cvt_pk_bf16_f32 v159, v6, v7
	ds_write_b64 v128, v[158:159] offset:25600
	v_cvt_pk_bf16_f32 v160, v0, v1
	v_cvt_pk_bf16_f32 v161, v2, v3
	ds_write_b64 v128, v[160:161] offset:25632
	s_waitcnt lgkmcnt(0)
	s_barrier
	ds_read_b128 v[184:187], v129
	ds_read_b128 v[188:191], v129 offset:1056
	ds_read_b128 v[192:195], v129 offset:2112
	ds_read_b128 v[196:199], v129 offset:3168
	ds_read_b128 v[200:203], v129 offset:4224
	ds_read_b128 v[204:207], v129 offset:5280
	ds_read_b128 v[208:211], v129 offset:6336
	ds_read_b128 v[212:215], v129 offset:7392
	s_waitcnt lgkmcnt(7)
	global_store_dwordx4 v130, v[184:187], s[20:21]
	v_add_u32_e32 v130, s24, v130
	s_waitcnt lgkmcnt(6)
	global_store_dwordx4 v130, v[188:191], s[20:21]
	v_add_u32_e32 v130, s24, v130
	s_waitcnt lgkmcnt(5)
	global_store_dwordx4 v130, v[192:195], s[20:21]
	v_add_u32_e32 v130, s24, v130
	s_waitcnt lgkmcnt(4)
	global_store_dwordx4 v130, v[196:199], s[20:21]
	v_add_u32_e32 v130, s24, v130
	s_waitcnt lgkmcnt(3)
	global_store_dwordx4 v130, v[200:203], s[20:21]
	v_add_u32_e32 v130, s24, v130
	s_waitcnt lgkmcnt(2)
	global_store_dwordx4 v130, v[204:207], s[20:21]
	v_add_u32_e32 v130, s24, v130
	s_waitcnt lgkmcnt(1)
	global_store_dwordx4 v130, v[208:211], s[20:21]
	v_add_u32_e32 v130, s24, v130
	s_waitcnt lgkmcnt(0)
	global_store_dwordx4 v130, v[212:215], s[20:21]
	v_readfirstlane_b32 s1, v180
	s_ashr_i32 s17, s1, 2
	s_andn2_b32 s17, s17, 63
	s_add_i32 s87, s87, s84
	s_cmpk_gt_i32 s87, 0x4ff
	s_waitcnt vmcnt(0)
	s_barrier
	s_cbranch_scc1 .LBB0_227

.LBB0_930:
	v_readlane_b32 s66, v254, 18
	v_readlane_b32 s67, v254, 19
	v_readlane_b32 s64, v254, 16
	v_readlane_b32 s65, v254, 17
	v_and_b32_e32 v131, 63, v180
	v_lshrrev_b32_e32 v132, 6, v180
	v_and_b32_e32 v133, 15, v131
	v_lshrrev_b32_e32 v134, 4, v131
	v_lshrrev_b32_e32 v135, 2, v132
	v_and_b32_e32 v136, 3, v132
	v_lshl_add_u32 v128, v135, 6, v133
	v_mul_u32_u24_e32 v128, 0x210, v128
	v_lshl_add_u32 v128, v136, 6, v128
	v_lshl_add_u32 v128, v134, 3, v128
	v_lshrrev_b32_e32 v137, 5, v131
	v_lshl_add_u32 v137, v132, 4, v137
	v_mul_u32_u24_e32 v129, 0x210, v137
	v_and_b32_e32 v138, 31, v131
	v_lshl_add_u32 v129, v138, 4, v129
	v_mul_u32_u24_e32 v130, 0x5040, v137
	v_lshl_add_u32 v130, v138, 4, v130
	s_mul_i32 s1, s24, 0x5040
	s_lshl_b32 s73, s0, 1
	s_add_u32 s1, s1, s73
	s_add_u32 s70, s66, s1
	s_addc_u32 s71, s67, 0
	s_mov_b32 s72, 0xa080
	v_cvt_pk_bf16_f32 v146, v124, v125
	v_cvt_pk_bf16_f32 v147, v126, v127
	ds_write_b64 v128, v[146:147]
	v_cvt_pk_bf16_f32 v148, v120, v121
	v_cvt_pk_bf16_f32 v149, v122, v123
	ds_write_b64 v128, v[148:149] offset:32
	v_cvt_pk_bf16_f32 v150, v116, v117
	v_cvt_pk_bf16_f32 v151, v118, v119
	ds_write_b64 v128, v[150:151] offset:256
	v_cvt_pk_bf16_f32 v152, v112, v113
	v_cvt_pk_bf16_f32 v153, v114, v115
	ds_write_b64 v128, v[152:153] offset:288
	v_cvt_pk_bf16_f32 v154, v108, v109
	v_cvt_pk_bf16_f32 v155, v110, v111
	ds_write_b64 v128, v[154:155] offset:8448
	v_cvt_pk_bf16_f32 v156, v104, v105
	v_cvt_pk_bf16_f32 v157, v106, v107
	ds_write_b64 v128, v[156:157] offset:8480
	v_cvt_pk_bf16_f32 v158, v100, v101
	v_cvt_pk_bf16_f32 v159, v102, v103
	ds_write_b64 v128, v[158:159] offset:8704
	v_cvt_pk_bf16_f32 v160, v96, v97
	v_cvt_pk_bf16_f32 v161, v98, v99
	ds_write_b64 v128, v[160:161] offset:8736
	v_cvt_pk_bf16_f32 v146, v92, v93
	v_cvt_pk_bf16_f32 v147, v94, v95
	ds_write_b64 v128, v[146:147] offset:16896
	v_cvt_pk_bf16_f32 v148, v88, v89
	v_cvt_pk_bf16_f32 v149, v90, v91
	ds_write_b64 v128, v[148:149] offset:16928
	v_cvt_pk_bf16_f32 v150, v84, v85
	v_cvt_pk_bf16_f32 v151, v86, v87
	ds_write_b64 v128, v[150:151] offset:17152
	v_cvt_pk_bf16_f32 v152, v80, v81
	v_cvt_pk_bf16_f32 v153, v82, v83
	ds_write_b64 v128, v[152:153] offset:17184
	v_cvt_pk_bf16_f32 v154, v76, v77
	v_cvt_pk_bf16_f32 v155, v78, v79
	ds_write_b64 v128, v[154:155] offset:25344
	v_cvt_pk_bf16_f32 v156, v72, v73
	v_cvt_pk_bf16_f32 v157, v74, v75
	ds_write_b64 v128, v[156:157] offset:25376
	v_cvt_pk_bf16_f32 v158, v68, v69
	v_cvt_pk_bf16_f32 v159, v70, v71
	ds_write_b64 v128, v[158:159] offset:25600
	v_cvt_pk_bf16_f32 v160, v64, v65
	v_cvt_pk_bf16_f32 v161, v66, v67
	ds_write_b64 v128, v[160:161] offset:25632
	s_waitcnt lgkmcnt(0)
	s_barrier
	ds_read_b128 v[184:187], v129
	ds_read_b128 v[188:191], v129 offset:1056
	ds_read_b128 v[192:195], v129 offset:2112
	ds_read_b128 v[196:199], v129 offset:3168
	ds_read_b128 v[200:203], v129 offset:4224
	ds_read_b128 v[204:207], v129 offset:5280
	ds_read_b128 v[208:211], v129 offset:6336
	ds_read_b128 v[212:215], v129 offset:7392
	s_waitcnt lgkmcnt(7)
	global_store_dwordx4 v130, v[184:187], s[70:71]
	v_add_u32_e32 v130, s72, v130
	s_waitcnt lgkmcnt(6)
	global_store_dwordx4 v130, v[188:191], s[70:71]
	v_add_u32_e32 v130, s72, v130
	s_waitcnt lgkmcnt(5)
	global_store_dwordx4 v130, v[192:195], s[70:71]
	v_add_u32_e32 v130, s72, v130
	s_waitcnt lgkmcnt(4)
	global_store_dwordx4 v130, v[196:199], s[70:71]
	v_add_u32_e32 v130, s72, v130
	s_waitcnt lgkmcnt(3)
	global_store_dwordx4 v130, v[200:203], s[70:71]
	v_add_u32_e32 v130, s72, v130
	s_waitcnt lgkmcnt(2)
	global_store_dwordx4 v130, v[204:207], s[70:71]
	v_add_u32_e32 v130, s72, v130
	s_waitcnt lgkmcnt(1)
	global_store_dwordx4 v130, v[208:211], s[70:71]
	v_add_u32_e32 v130, s72, v130
	s_waitcnt lgkmcnt(0)
	global_store_dwordx4 v130, v[212:215], s[70:71]
	v_add_u32_e32 v130, s72, v130
	v_add_u32_e32 v130, 0x231c00, v130
	s_barrier
	v_cvt_pk_bf16_f32 v146, v60, v61
	v_cvt_pk_bf16_f32 v147, v62, v63
	ds_write_b64 v128, v[146:147]
	v_cvt_pk_bf16_f32 v148, v56, v57
	v_cvt_pk_bf16_f32 v149, v58, v59
	ds_write_b64 v128, v[148:149] offset:32
	v_cvt_pk_bf16_f32 v150, v52, v53
	v_cvt_pk_bf16_f32 v151, v54, v55
	ds_write_b64 v128, v[150:151] offset:256
	v_cvt_pk_bf16_f32 v152, v48, v49
	v_cvt_pk_bf16_f32 v153, v50, v51
	ds_write_b64 v128, v[152:153] offset:288
	v_cvt_pk_bf16_f32 v154, v44, v45
	v_cvt_pk_bf16_f32 v155, v46, v47
	ds_write_b64 v128, v[154:155] offset:8448
	v_cvt_pk_bf16_f32 v156, v40, v41
	v_cvt_pk_bf16_f32 v157, v42, v43
	ds_write_b64 v128, v[156:157] offset:8480
	v_cvt_pk_bf16_f32 v158, v36, v37
	v_cvt_pk_bf16_f32 v159, v38, v39
	ds_write_b64 v128, v[158:159] offset:8704
	v_cvt_pk_bf16_f32 v160, v32, v33
	v_cvt_pk_bf16_f32 v161, v34, v35
	ds_write_b64 v128, v[160:161] offset:8736
	v_cvt_pk_bf16_f32 v146, v28, v29
	v_cvt_pk_bf16_f32 v147, v30, v31
	ds_write_b64 v128, v[146:147] offset:16896
	v_cvt_pk_bf16_f32 v148, v24, v25
	v_cvt_pk_bf16_f32 v149, v26, v27
	ds_write_b64 v128, v[148:149] offset:16928
	v_cvt_pk_bf16_f32 v150, v20, v21
	v_cvt_pk_bf16_f32 v151, v22, v23
	ds_write_b64 v128, v[150:151] offset:17152
	v_cvt_pk_bf16_f32 v152, v16, v17
	v_cvt_pk_bf16_f32 v153, v18, v19
	ds_write_b64 v128, v[152:153] offset:17184
	v_cvt_pk_bf16_f32 v154, v12, v13
	v_cvt_pk_bf16_f32 v155, v14, v15
	ds_write_b64 v128, v[154:155] offset:25344
	v_cvt_pk_bf16_f32 v156, v8, v9
	v_cvt_pk_bf16_f32 v157, v10, v11
	ds_write_b64 v128, v[156:157] offset:25376
	v_cvt_pk_bf16_f32 v158, v4, v5
	v_cvt_pk_bf16_f32 v159, v6, v7
	ds_write_b64 v128, v[158:159] offset:25600
	v_cvt_pk_bf16_f32 v160, v0, v1
	v_cvt_pk_bf16_f32 v161, v2, v3
	ds_write_b64 v128, v[160:161] offset:25632
	s_waitcnt lgkmcnt(0)
	s_barrier
	ds_read_b128 v[184:187], v129
	ds_read_b128 v[188:191], v129 offset:1056
	ds_read_b128 v[192:195], v129 offset:2112
	ds_read_b128 v[196:199], v129 offset:3168
	ds_read_b128 v[200:203], v129 offset:4224
	ds_read_b128 v[204:207], v129 offset:5280
	ds_read_b128 v[208:211], v129 offset:6336
	ds_read_b128 v[212:215], v129 offset:7392
	s_waitcnt lgkmcnt(7)
	global_store_dwordx4 v130, v[184:187], s[70:71]
	v_add_u32_e32 v130, s72, v130
	s_waitcnt lgkmcnt(6)
	global_store_dwordx4 v130, v[188:191], s[70:71]
	v_add_u32_e32 v130, s72, v130
	s_waitcnt lgkmcnt(5)
	global_store_dwordx4 v130, v[192:195], s[70:71]
	v_add_u32_e32 v130, s72, v130
	s_waitcnt lgkmcnt(4)
	global_store_dwordx4 v130, v[196:199], s[70:71]
	v_add_u32_e32 v130, s72, v130
	s_waitcnt lgkmcnt(3)
	global_store_dwordx4 v130, v[200:203], s[70:71]
	v_add_u32_e32 v130, s72, v130
	s_waitcnt lgkmcnt(2)
	global_store_dwordx4 v130, v[204:207], s[70:71]
	v_add_u32_e32 v130, s72, v130
	s_waitcnt lgkmcnt(1)
	global_store_dwordx4 v130, v[208:211], s[70:71]
	v_add_u32_e32 v130, s72, v130
	s_waitcnt lgkmcnt(0)
	global_store_dwordx4 v130, v[212:215], s[70:71]
	v_readfirstlane_b32 s1, v180
	s_ashr_i32 s25, s1, 2
	s_andn2_b32 s25, s25, 63
	s_add_i32 s58, s58, s94
	s_cmpk_gt_i32 s58, 0x4ff
	s_waitcnt vmcnt(0)
	s_barrier
	s_cbranch_scc1 .LBB0_937
